# prologue x-norm loop hand-written (row loads together, gain in registers) on top of the loop-edge rotation
# speedup vs baseline: 1.0060x; 1.0006x over previous
; __device__ __forceinline__ u32x4 pack8(f32x4 a, f32x4 b) { u32x4 o; o.x = pk2(a[0], a[1]); o.y = pk2(a[2], a[3]); o.z = pk2(b[0], b[1]); o.w = pk2(b[2], b[3]); return o; }
; __device__ __forceinline__ void norm_row(const float* xrow, const float* g, bf16_t* xn, int lane) {
;     f32x4 h[4][2]; float s2 = 0.f;
; #pragma unroll
;     for (int j = 0; j < 4; ++j)
; #pragma unroll
;         for (int q = 0; q < 2; ++q) { h[j][q] = *(const f32x4*)(xrow + 512 * j + 8 * lane + 4 * q);
; #pragma unroll
;             for (int i = 0; i < 4; ++i) s2 += h[j][q][i] * h[j][q][i]; }
;     const float r2 = __frsqrt_rn(wave_sum(s2) * (1.f / DM) + EPS);
; #pragma unroll
;     for (int j = 0; j < 4; ++j) { const int c = 512 * j + 8 * lane; const f32x4 g0 = *(const f32x4*)(g + c), g1 = *(const f32x4*)(g + c + 4);
;         *(u32x4*)(xn + c) = pack8(h[j][0] * r2 * g0, h[j][1] * r2 * g1); }
; }
; __global__ void __launch_bounds__(NTHREADS, 2) fwd_kernel(Params P) {
;     ...
;         for (int m = gw; m < MTOK; m += NGW) norm_row(x + (size_t)m * DM, P.in[1], XN + (size_t)m * DM, lane);
.LBB0_131:
	s_cmpk_gt_i32 s6, 0x7fff
	v_mbcnt_lo_u32_b32 v182, -1, 0
	s_cbranch_scc1 .LBB0_134
	s_waitcnt lgkmcnt(0)
	v_and_b32_e32 v25, 63, v180
	v_lshlrev_b32_e32 v16, 4, v25
	v_lshlrev_b32_e32 v19, 5, v25
	v_add_u32_e32 v20, 0x1000, v19
	s_lshl_b32 s7, s6, 12
	v_add_u32_e32 v16, s7, v16
	s_lshl_b32 s7, s6, 13
	v_add_u32_e32 v17, s7, v19
	v_add_u32_e32 v18, 0x1000, v17
	s_add_u32 s4, s30, 0xb900000
	s_addc_u32 s5, s31, 0
	global_load_dwordx4 v[152:155], v19, s[10:11] offset:0
	global_load_dwordx4 v[156:159], v19, s[10:11] offset:16
	global_load_dwordx4 v[160:163], v19, s[10:11] offset:2048
	global_load_dwordx4 v[164:167], v19, s[10:11] offset:2064
	global_load_dwordx4 v[168:171], v20, s[10:11] offset:0
	global_load_dwordx4 v[172:175], v20, s[10:11] offset:16
	global_load_dwordx4 v[176:179], v20, s[10:11] offset:2048
	global_load_dwordx4 v[188:191], v20, s[10:11] offset:2064
	v_mov_b32_e32 v21, 0x358637bd
.Lrow_top_p0n:
	global_load_dwordx4 v[56:59], v17, s[8:9] offset:0
	global_load_dwordx4 v[60:63], v17, s[8:9] offset:16
	global_load_dwordx4 v[64:67], v17, s[8:9] offset:2048
	global_load_dwordx4 v[68:71], v17, s[8:9] offset:2064
	global_load_dwordx4 v[72:75], v18, s[8:9] offset:0
	global_load_dwordx4 v[76:79], v18, s[8:9] offset:16
	global_load_dwordx4 v[80:83], v18, s[8:9] offset:2048
	global_load_dwordx4 v[84:87], v18, s[8:9] offset:2064
	s_waitcnt vmcnt(0)
	v_mul_f32_e32 v26, v56, v56
	v_mul_f32_e32 v27, v64, v64
	v_mul_f32_e32 v29, v72, v72
	v_mul_f32_e32 v31, v80, v80
	v_fmac_f32_e32 v26, v57, v57
	v_fmac_f32_e32 v27, v65, v65
	v_fmac_f32_e32 v29, v73, v73
	v_fmac_f32_e32 v31, v81, v81
	v_fmac_f32_e32 v26, v58, v58
	v_fmac_f32_e32 v27, v66, v66
	v_fmac_f32_e32 v29, v74, v74
	v_fmac_f32_e32 v31, v82, v82
	v_fmac_f32_e32 v26, v59, v59
	v_fmac_f32_e32 v27, v67, v67
	v_fmac_f32_e32 v29, v75, v75
	v_fmac_f32_e32 v31, v83, v83
	v_fmac_f32_e32 v26, v60, v60
	v_fmac_f32_e32 v27, v68, v68
	v_fmac_f32_e32 v29, v76, v76
	v_fmac_f32_e32 v31, v84, v84
	v_fmac_f32_e32 v26, v61, v61
	v_fmac_f32_e32 v27, v69, v69
	v_fmac_f32_e32 v29, v77, v77
	v_fmac_f32_e32 v31, v85, v85
	v_fmac_f32_e32 v26, v62, v62
	v_fmac_f32_e32 v27, v70, v70
	v_fmac_f32_e32 v29, v78, v78
	v_fmac_f32_e32 v31, v86, v86
	v_fmac_f32_e32 v26, v63, v63
	v_fmac_f32_e32 v27, v71, v71
	v_fmac_f32_e32 v29, v79, v79
	v_fmac_f32_e32 v31, v87, v87
	v_add_f32_e32 v26, v26, v27
	v_add_f32_e32 v29, v29, v31
	v_add_f32_e32 v23, v26, v29
	s_nop 1
	v_add_f32_dpp v23, v23, v23 quad_perm:[1,0,3,2] row_mask:0xf bank_mask:0xf
	s_nop 1
	v_add_f32_dpp v23, v23, v23 quad_perm:[2,3,0,1] row_mask:0xf bank_mask:0xf
	s_nop 1
	v_add_f32_dpp v23, v23, v23 row_half_mirror row_mask:0xf bank_mask:0xf
	s_nop 1
	v_add_f32_dpp v23, v23, v23 row_mirror row_mask:0xf bank_mask:0xf
	ds_swizzle_b32 v24, v23 offset:0x401f
	s_waitcnt lgkmcnt(0)
	v_add_f32_e32 v23, v23, v24
	v_mov_b32_e32 v24, v23
	s_nop 1
	v_permlane32_swap_b32_e32 v23, v24
	v_add_f32_e32 v23, v23, v24
	v_fmamk_f32 v23, v23, 0x3a000000, v21
	v_rsq_f32_e32 v23, v23
	s_nop 0
	v_mul_f32_e32 v88, v56, v23
	v_mul_f32_e32 v89, v57, v23
	v_mul_f32_e32 v90, v58, v23
	v_mul_f32_e32 v91, v59, v23
	v_mul_f32_e32 v92, v60, v23
	v_mul_f32_e32 v93, v61, v23
	v_mul_f32_e32 v94, v62, v23
	v_mul_f32_e32 v95, v63, v23
	v_mul_f32_e32 v96, v64, v23
	v_mul_f32_e32 v97, v65, v23
	v_mul_f32_e32 v98, v66, v23
	v_mul_f32_e32 v99, v67, v23
	v_mul_f32_e32 v100, v68, v23
	v_mul_f32_e32 v101, v69, v23
	v_mul_f32_e32 v102, v70, v23
	v_mul_f32_e32 v103, v71, v23
	v_mul_f32_e32 v104, v72, v23
	v_mul_f32_e32 v105, v73, v23
	v_mul_f32_e32 v106, v74, v23
	v_mul_f32_e32 v107, v75, v23
	v_mul_f32_e32 v108, v76, v23
	v_mul_f32_e32 v109, v77, v23
	v_mul_f32_e32 v110, v78, v23
	v_mul_f32_e32 v111, v79, v23
	v_mul_f32_e32 v112, v80, v23
	v_mul_f32_e32 v113, v81, v23
	v_mul_f32_e32 v114, v82, v23
	v_mul_f32_e32 v115, v83, v23
	v_mul_f32_e32 v116, v84, v23
	v_mul_f32_e32 v117, v85, v23
	v_mul_f32_e32 v118, v86, v23
	v_mul_f32_e32 v119, v87, v23
	v_mul_f32_e32 v88, v152, v88
	v_mul_f32_e32 v89, v153, v89
	v_mul_f32_e32 v90, v154, v90
	v_mul_f32_e32 v91, v155, v91
	v_mul_f32_e32 v92, v156, v92
	v_mul_f32_e32 v93, v157, v93
	v_mul_f32_e32 v94, v158, v94
	v_mul_f32_e32 v95, v159, v95
	v_mul_f32_e32 v96, v160, v96
	v_mul_f32_e32 v97, v161, v97
	v_mul_f32_e32 v98, v162, v98
	v_mul_f32_e32 v99, v163, v99
	v_mul_f32_e32 v100, v164, v100
	v_mul_f32_e32 v101, v165, v101
	v_mul_f32_e32 v102, v166, v102
	v_mul_f32_e32 v103, v167, v103
	v_mul_f32_e32 v104, v168, v104
	v_mul_f32_e32 v105, v169, v105
	v_mul_f32_e32 v106, v170, v106
	v_mul_f32_e32 v107, v171, v107
	v_mul_f32_e32 v108, v172, v108
	v_mul_f32_e32 v109, v173, v109
	v_mul_f32_e32 v110, v174, v110
	v_mul_f32_e32 v111, v175, v111
	v_mul_f32_e32 v112, v176, v112
	v_mul_f32_e32 v113, v177, v113
	v_mul_f32_e32 v114, v178, v114
	v_mul_f32_e32 v115, v179, v115
	v_mul_f32_e32 v116, v188, v116
	v_mul_f32_e32 v117, v189, v117
	v_mul_f32_e32 v118, v190, v118
	v_mul_f32_e32 v119, v191, v119
	v_cvt_pk_bf16_f32 v32, v88, v89
	v_cvt_pk_bf16_f32 v33, v90, v91
	v_cvt_pk_bf16_f32 v34, v92, v93
	v_cvt_pk_bf16_f32 v35, v94, v95
	v_cvt_pk_bf16_f32 v36, v96, v97
	v_cvt_pk_bf16_f32 v37, v98, v99
	v_cvt_pk_bf16_f32 v38, v100, v101
	v_cvt_pk_bf16_f32 v39, v102, v103
	v_cvt_pk_bf16_f32 v40, v104, v105
	v_cvt_pk_bf16_f32 v41, v106, v107
	v_cvt_pk_bf16_f32 v42, v108, v109
	v_cvt_pk_bf16_f32 v43, v110, v111
	v_cvt_pk_bf16_f32 v44, v112, v113
	v_cvt_pk_bf16_f32 v45, v114, v115
	v_cvt_pk_bf16_f32 v46, v116, v117
	v_cvt_pk_bf16_f32 v47, v118, v119
	global_store_dwordx4 v16, v[32:35], s[4:5] offset:0
	global_store_dwordx4 v16, v[36:39], s[4:5] offset:1024
	global_store_dwordx4 v16, v[40:43], s[4:5] offset:2048
	global_store_dwordx4 v16, v[44:47], s[4:5] offset:3072
	s_lshl_b32 s7, s26, 12
	s_nop 0
	v_add_u32_e32 v16, s7, v16
	s_lshl_b32 s7, s26, 13
	v_add_u32_e32 v17, s7, v17
	v_add_u32_e32 v18, s7, v18
	s_add_i32 s6, s6, s26
	s_cmpk_gt_i32 s6, 0x7fff
	s_cbranch_scc0 .Lrow_top_p0n
	s_nop 4
